# scan L2 prefetch: C and B tiles plus 16 dt rows per wave (3 LDS-DMA dword loads per wave in l-tile 5)
# speedup vs baseline: 1.0063x; 1.0063x over previous
; #define LAS __attribute__((address_space(3)))
; template <int MODE> __device__ __forceinline__ void ssd_scan_phase(Frame& F, int j, bool ctx_out) {
;     ...
;                     const int l = 16 * lt + fr; const float cl = tab[l];
;                     f32x4 accd[2], acco[2];
;                     accd[0] = accd[1] = acco[0] = acco[1] = (f32x4){0.f, 0.f, 0.f, 0.f};
;                     const int kd = lt >> 1;
;                     if ((lt & 1) == 0) { xb_cur = xb_nxt; if (kd + 1 < 4) xb_nxt = *(const bf16x8*)(xl + (size_t)16 * T + 32 * (kd + 1)); }
;                     const bf16x8 xa = xf[0][kd], xb = xb_cur;
; #pragma unroll
;                     for (int ks = 0; ks < 4; ++ks) {
;                         const bool full = dir == 0 ? (ks < kd) : (ks > kd);
;                         if (full) {
;                             const bf16x8 gf = *(const LAS bf16x8*)(GS + l * 256 + (((4 * ks + fq) ^ fr) << 4));
;                             const float f1 = __builtin_amdgcn_exp2f(cl - tab[dir == 0 ? 32 * ks + 31 : 32 * ks]);
;                             const f32x4 z4 = (f32x4){0.f, 0.f, 0.f, 0.f};
;                             const f32x4 t0 = __builtin_amdgcn_mfma_f32_16x16x32_bf16(xs2[0][ks], gf, z4, 0, 0, 0), t1 = __builtin_amdgcn_mfma_f32_16x16x32_bf16(xs2[1][ks], gf, z4, 0, 0, 0);
;                             accd[0] += t0 * f1; accd[1] += t1 * f1;
;                         }
;                     }
; #pragma unroll
;                     for (int q = 0; q < 4; ++q) {
;                         const u32x2 lo = *(const LAS u32x2*)(CS + l * 256 + (((4 * q + (fq >> 1)) ^ fr) << 4) + (fq & 1) * 8), hi = *(const LAS u32x2*)(CS + l * 256 + (((4 * q + 2 + (fq >> 1)) ^ fr) << 4) + (fq & 1) * 8);
;                         u32x4 c4; c4.x = lo.x; c4.y = lo.y; c4.z = hi.x; c4.w = hi.y; const bf16x8 cfr = __builtin_bit_cast(bf16x8, c4);
;                         acco[0] = __builtin_amdgcn_mfma_f32_16x16x32_bf16(hf[0][q], cfr, acco[0], 0, 0, 0);
;                         acco[1] = __builtin_amdgcn_mfma_f32_16x16x32_bf16(hf[1][q], cfr, acco[1], 0, 0, 0);
;                     }
;     ...
;                 const int kn = k + 1; const bool isctxn = kn < 2; const int ccn = isctxn ? (dir == 0 ? kn : 1 - kn) : (dir == 0 ? kn - 2 : 17 - kn);
;                 const int row0n = isctxn ? MLAT + b * LCTX + ccn * 128 : b * LSEQ + ccn * 128;
.LBB0_514:
	v_mbcnt_lo_u32_b32 v179, -1, 0
	v_mbcnt_hi_u32_b32 v179, -1, v179
	s_sub_i32 s100, s4, 1
	s_sub_i32 s101, 16, s4
	s_cmp_lg_u32 s38, 0
	s_cselect_b32 s100, s100, s101
	s_lshl_b32 s100, s100, 7
	s_add_i32 s100, s100, s81
	s_cmp_eq_u32 s4, 0
	s_cselect_b32 s100, s76, s100
	s_cmp_eq_u32 s4, 17
	s_cselect_b32 s100, s81, s100
	s_sub_i32 s101, s18, 0x18000
	s_lshr_b32 s101, s101, 7
	s_add_i32 s101, s101, s100
	v_and_b32_e32 v178, 3, v179
	v_lshl_add_u32 v178, v178, 5, v188
	v_and_b32_e32 v220, 4, v179
	v_lshlrev_b32_e32 v178, 11, v178
	v_lshl_add_u32 v178, v220, 5, v178
	v_and_b32_e32 v221, 15, v179
	v_add_u32_e32 v221, s101, v221
	v_lshlrev_b32_e32 v221, 9, v221
	s_lshl_b32 s100, s100, 11
	v_add_u32_e32 v178, s100, v178
	s_mov_b32 m0, 0x1c000
	s_mov_b32 s100, s77
	s_mov_b32 s101, s73
	global_load_lds_dword v178, s[100:101]
	global_load_lds_dword v178, s[74:75]
	global_load_lds_dword v221, s[34:35]
	v_add3_u32 v178, 0, v218, v195
	v_add_u32_e32 v179, v178, v185
	ds_read_b64 v[218:219], v179
	v_add_u32_e32 v179, v178, v183
	ds_read_b64 v[220:221], v179
	v_add_u32_e32 v179, v178, v187
	ds_read_b64 v[226:227], v179
	v_add_u32_e32 v179, v178, v213
	ds_read_b64 v[228:229], v179
	s_waitcnt lgkmcnt(2)
	v_mfma_f32_16x16x32_bf16 v[222:225], v[116:119], v[218:221], 0
	v_add_u32_e32 v179, v178, v212
	ds_read_b64 v[230:231], v179
	v_add_u32_e32 v179, v178, v211
	v_mfma_f32_16x16x32_bf16 v[218:221], v[124:127], v[218:221], 0
	ds_read_b64 v[232:233], v179
	v_add_u32_e32 v179, v178, v191
	v_add_u32_e32 v178, v178, v210
	s_waitcnt lgkmcnt(2)
	v_mfma_f32_16x16x32_bf16 v[222:225], v[112:115], v[226:229], v[222:225]
	v_add_u32_e32 v170, v170, v168
	v_sub_f32_e32 v164, v171, v164
	v_exp_f32_e32 v164, v164
	v_mfma_f32_16x16x32_bf16 v[218:221], v[120:123], v[226:229], v[218:221]
	ds_read_b64 v[226:227], v179
	ds_read_b64 v[228:229], v178
	v_sub_f32_e32 v165, v171, v165
	s_waitcnt lgkmcnt(2)
	v_mfma_f32_16x16x32_bf16 v[222:225], v[108:111], v[230:233], v[222:225]
	v_exp_f32_e32 v165, v165
	v_sub_f32_e32 v166, v171, v166
	v_exp_f32_e32 v166, v166
	v_mfma_f32_16x16x32_bf16 v[218:221], v[128:131], v[230:233], v[218:221]
	ds_read_b128 v[230:233], v170
	v_add_u32_e32 v170, 64, v180
	s_waitcnt lgkmcnt(1)
	v_mfma_f32_16x16x32_bf16 v[222:225], v[104:107], v[226:229], v[222:225]
	s_waitcnt lgkmcnt(0)
; #define LAS __attribute__((address_space(3)))
; __device__ __forceinline__ unsigned cvt_pk_bf16(float lo, float hi) { const f32x2 v = {lo, hi}; return __builtin_bit_cast(unsigned, __builtin_convertvector(v, bf16x2_t)); }
; __device__ __forceinline__ u32x4 pack8(const float (&f)[8]) { u32x4 w; w.x = cvt_pk_bf16(f[0], f[1]); w.y = cvt_pk_bf16(f[2], f[3]); w.z = cvt_pk_bf16(f[4], f[5]); w.w = cvt_pk_bf16(f[6], f[7]); return w; }
; template <int MODE> __device__ __forceinline__ void ssd_scan_phase(Frame& F, int j, bool ctx_out) {
;     ...
;                         float gg[8]; unpack8(*(const LAS u32x4*)(GS + l * 256 + (((4 * kd + fq) ^ fr) << 4)), gg);
;                         const f32x4 ca = *(const LAS f32x4*)(tab + 32 * kd + 8 * fq), cb = *(const LAS f32x4*)(tab + 32 * kd + 8 * fq + 4);
;                         const f32x4 da = *(const LAS f32x4*)(tab + 128 + 32 * kd + 8 * fq), db = *(const LAS f32x4*)(tab + 128 + 32 * kd + 8 * fq + 4);
;                         const float cs[8] = {ca.x, ca.y, ca.z, ca.w, cb.x, cb.y, cb.z, cb.w}, ds[8] = {da.x, da.y, da.z, da.w, db.x, db.y, db.z, db.w};
;                         float m[8];
; #pragma unroll
;                         for (int jj = 0; jj < 8; ++jj) { const int s = 32 * kd + 8 * fq + jj; const bool valid = dir == 0 ? (s <= l) : (s >= l);
;                             const float e = valid ? __builtin_amdgcn_exp2f(cl - cs[jj]) : 0.f; m[jj] = gg[jj] * e * ds[jj]; if (dir == 0 && s == l) m[jj] += dsk; }
;                         const bf16x8 mf = __builtin_bit_cast(bf16x8, pack8(m));
;                         accd[0] = __builtin_amdgcn_mfma_f32_16x16x32_bf16(xa, mf, accd[0], 0, 0, 0);
;                         accd[1] = __builtin_amdgcn_mfma_f32_16x16x32_bf16(xb, mf, accd[1], 0, 0, 0);
;                     }
;                     const float el = __builtin_amdgcn_exp2f(cl);
; #pragma unroll
;                     for (int pt = 0; pt < 2; ++pt) { const f32x4 y = accd[pt] + acco[pt] * el; u32x2 o; o.x = cvt_pk_bf16(y[0], y[1]); o.y = cvt_pk_bf16(y[2], y[3]);
;                         *(u32x2*)(yout + (size_t)(row0 + l) * DI + h * 64 + ph * 32 + 16 * pt + 4 * fq) = o; }
;                 }
	v_lshlrev_b32_e32 v178, 16, v230
	v_and_b32_e32 v179, 0xffff0000, v230
	v_lshlrev_b32_e32 v230, 16, v233
	v_mfma_f32_16x16x32_bf16 v[218:221], v[132:135], v[226:229], v[218:221]
	v_lshlrev_b32_e32 v226, 16, v231
	v_and_b32_e32 v227, 0xffff0000, v231
	v_lshlrev_b32_e32 v228, 16, v232
	v_and_b32_e32 v229, 0xffff0000, v232
	v_and_b32_e32 v231, 0xffff0000, v233
	v_cmp_le_i32_e32 vcc, v170, v169
	v_cmp_eq_u32_e64 s[100:101], v170, v169
	s_xnor_b64 vcc, vcc, s[38:39]
	s_andn2_b64 s[100:101], s[100:101], s[38:39]
	s_or_b64 vcc, vcc, s[100:101]
	v_sub_f32_e32 v156, v171, v156
	v_cndmask_b32_e32 v164, 0, v164, vcc
	v_mul_f32_e32 v164, v164, v178
	v_cmp_eq_u32_e32 vcc, v170, v169
	v_mul_f32_e32 v178, v160, v164
	s_and_b64 vcc, s[38:39], vcc
	v_fma_f32 v160, v160, v164, v203
	v_cndmask_b32_e32 v160, v178, v160, vcc
	v_cmp_le_i32_e32 vcc, v173, v169
	v_cmp_eq_u32_e64 s[100:101], v173, v169
	s_xnor_b64 vcc, vcc, s[38:39]
	s_andn2_b64 s[100:101], s[100:101], s[38:39]
	s_or_b64 vcc, vcc, s[100:101]
	v_exp_f32_e32 v156, v156
	v_sub_f32_e32 v157, v171, v157
	v_cndmask_b32_e32 v164, 0, v165, vcc
	v_mul_f32_e32 v164, v164, v179
	v_cmp_eq_u32_e32 vcc, v173, v169
	v_mul_f32_e32 v165, v161, v164
	s_and_b64 vcc, s[38:39], vcc
	v_fma_f32 v161, v161, v164, v203
	v_cndmask_b32_e32 v161, v165, v161, vcc
	v_cmp_le_i32_e32 vcc, v174, v169
	v_cmp_eq_u32_e64 s[100:101], v174, v169
	s_xnor_b64 vcc, vcc, s[38:39]
	s_andn2_b64 s[100:101], s[100:101], s[38:39]
	s_or_b64 vcc, vcc, s[100:101]
	v_exp_f32_e32 v157, v157
	v_sub_f32_e32 v158, v171, v158
	v_cndmask_b32_e32 v164, 0, v166, vcc
	v_mul_f32_e32 v164, v164, v226
	v_cmp_eq_u32_e32 vcc, v174, v169
	v_mul_f32_e32 v165, v162, v164
	s_and_b64 vcc, s[38:39], vcc
	v_fma_f32 v162, v162, v164, v203
	v_cndmask_b32_e32 v162, v165, v162, vcc
	v_sub_f32_e32 v166, v171, v167
	v_exp_f32_e32 v166, v166
	v_cmp_le_i32_e32 vcc, v175, v169
	v_cmp_eq_u32_e64 s[100:101], v175, v169
	s_xnor_b64 vcc, vcc, s[38:39]
	s_andn2_b64 s[100:101], s[100:101], s[38:39]
	s_or_b64 vcc, vcc, s[100:101]
	v_exp_f32_e32 v158, v158
	v_cndmask_b32_e32 v164, 0, v166, vcc
	v_mul_f32_e32 v164, v164, v227
	v_cmp_eq_u32_e32 vcc, v175, v169
	v_mul_f32_e32 v165, v163, v164
	s_and_b64 vcc, s[38:39], vcc
	v_fma_f32 v163, v163, v164, v203
	v_cndmask_b32_e32 v163, v165, v163, vcc
	v_cmp_le_i32_e32 vcc, v200, v169
	v_cmp_eq_u32_e64 s[100:101], v200, v169
	s_xnor_b64 vcc, vcc, s[38:39]
	s_andn2_b64 s[100:101], s[100:101], s[38:39]
	s_or_b64 vcc, vcc, s[100:101]
	s_mov_b32 s94, s92
	s_mov_b32 s95, s92
	v_cndmask_b32_e32 v156, 0, v156, vcc
	v_mul_f32_e32 v156, v156, v228
	v_cmp_eq_u32_e32 vcc, v200, v169
	v_mul_f32_e32 v164, v152, v156
	s_and_b64 vcc, s[38:39], vcc
	v_fma_f32 v152, v152, v156, v203
	v_cndmask_b32_e32 v156, v164, v152, vcc
	v_cmp_le_i32_e32 vcc, v201, v169
	v_cmp_eq_u32_e64 s[100:101], v201, v169
	s_xnor_b64 vcc, vcc, s[38:39]
	s_andn2_b64 s[100:101], s[100:101], s[38:39]
	s_or_b64 vcc, vcc, s[100:101]
	s_mov_b32 s93, s92
	s_nop 0
	v_cndmask_b32_e32 v152, 0, v157, vcc
	v_mul_f32_e32 v152, v152, v229
	v_cmp_eq_u32_e32 vcc, v201, v169
	v_mul_f32_e32 v157, v153, v152
	s_and_b64 vcc, s[38:39], vcc
	v_fma_f32 v152, v153, v152, v203
	v_cndmask_b32_e32 v157, v157, v152, vcc
	v_cmp_le_i32_e32 vcc, v216, v169
	v_cmp_eq_u32_e64 s[100:101], v216, v169
	s_xnor_b64 vcc, vcc, s[38:39]
	s_andn2_b64 s[100:101], s[100:101], s[38:39]
	s_or_b64 vcc, vcc, s[100:101]
	v_cndmask_b32_e32 v152, 0, v158, vcc
	v_mul_f32_e32 v152, v152, v230
	v_cmp_eq_u32_e32 vcc, v216, v169
	v_mul_f32_e32 v153, v154, v152
	s_and_b64 vcc, s[38:39], vcc
	v_fma_f32 v152, v154, v152, v203
	v_cndmask_b32_e32 v158, v153, v152, vcc
	v_sub_f32_e32 v154, v171, v159
	v_exp_f32_e32 v154, v154
	v_cmp_le_i32_e32 vcc, v217, v169
	v_cmp_eq_u32_e64 s[100:101], v217, v169
	s_xnor_b64 vcc, vcc, s[38:39]
	s_andn2_b64 s[100:101], s[100:101], s[38:39]
	s_or_b64 vcc, vcc, s[100:101]
	v_cndmask_b32_e32 v152, 0, v154, vcc
	v_mul_f32_e32 v152, v152, v231
	v_cmp_eq_u32_e32 vcc, v217, v169
	v_mul_f32_e32 v153, v155, v152
	s_and_b64 vcc, s[38:39], vcc
	v_fma_f32 v152, v155, v152, v203
	v_cndmask_b32_e32 v155, v153, v152, vcc
	v_cvt_pk_bf16_f32 v152, v160, v161
	v_cvt_pk_bf16_f32 v153, v162, v163
	v_cvt_pk_bf16_f32 v154, v156, v157
	v_cvt_pk_bf16_f32 v155, v158, v155
	ds_read_b32 v161, v214 offset:384
	v_or_b32_e32 v160, 0x60, v176
	v_mfma_f32_16x16x32_bf16 v[144:147], v[100:103], v[152:155], v[144:147]
	v_mov_b64_e32 v[102:103], s[94:95]
	v_mov_b64_e32 v[100:101], s[92:93]
	s_and_b64 vcc, exec, s[46:47]
	v_mfma_f32_16x16x32_bf16 v[140:143], v[140:143], v[152:155], v[148:151]
	s_nop 2
	v_exp_f32_e32 v148, v171
	v_add_u32_e32 v150, s5, v169
	v_ashrrev_i32_e32 v151, 31, v150
	v_lshlrev_b64 v[150:151], 13, v[150:151]
	v_pk_fma_f32 v[146:147], v[148:149], v[224:225], v[146:147] op_sel_hi:[0,1,1]
	v_pk_fma_f32 v[144:145], v[148:149], v[222:223], v[144:145] op_sel_hi:[0,1,1]
	v_pk_fma_f32 v[142:143], v[148:149], v[220:221], v[142:143] op_sel_hi:[0,1,1]
	v_pk_fma_f32 v[140:141], v[148:149], v[218:219], v[140:141] op_sel_hi:[0,1,1]
	v_lshl_add_u64 v[150:151], v[198:199], 0, v[150:151]
	v_cvt_pk_bf16_f32 v144, v144, v145
	v_cvt_pk_bf16_f32 v145, v146, v147
	v_cvt_pk_bf16_f32 v140, v140, v141
	v_cvt_pk_bf16_f32 v141, v142, v143
	global_store_dwordx2 v[150:151], v[144:145], off
	global_store_dwordx2 v[150:151], v[140:141], off offset:32
	v_lshlrev_b32_e32 v141, 8, v160
	v_mov_b64_e32 v[150:151], s[94:95]
	v_add_u32_e32 v140, s87, v141
	v_mov_b64_e32 v[148:149], s[92:93]
	s_cbranch_vccz .LBB0_536
	s_and_b64 vcc, exec, s[46:47]
	s_cbranch_vccz .LBB0_537

; #define LAS __attribute__((address_space(3)))
; template <int MODE> __device__ __forceinline__ void ssd_scan_phase(Frame& F, int j, bool ctx_out) {
;     ...
;                     const int l = 16 * lt + fr; const float cl = tab[l];
;                     f32x4 accd[2], acco[2];
;                     accd[0] = accd[1] = acco[0] = acco[1] = (f32x4){0.f, 0.f, 0.f, 0.f};
;                     const int kd = lt >> 1;
;                     if ((lt & 1) == 0) { xb_cur = xb_nxt; if (kd + 1 < 4) xb_nxt = *(const bf16x8*)(xl + (size_t)16 * T + 32 * (kd + 1)); }
;                     const bf16x8 xa = xf[0][kd], xb = xb_cur;
; #pragma unroll
;                     for (int ks = 0; ks < 4; ++ks) {
;                         const bool full = dir == 0 ? (ks < kd) : (ks > kd);
;                         if (full) {
;                             const bf16x8 gf = *(const LAS bf16x8*)(GS + l * 256 + (((4 * ks + fq) ^ fr) << 4));
;                             const float f1 = __builtin_amdgcn_exp2f(cl - tab[dir == 0 ? 32 * ks + 31 : 32 * ks]);
;                             const f32x4 z4 = (f32x4){0.f, 0.f, 0.f, 0.f};
;                             const f32x4 t0 = __builtin_amdgcn_mfma_f32_16x16x32_bf16(xs2[0][ks], gf, z4, 0, 0, 0), t1 = __builtin_amdgcn_mfma_f32_16x16x32_bf16(xs2[1][ks], gf, z4, 0, 0, 0);
;                             accd[0] += t0 * f1; accd[1] += t1 * f1;
;                         }
;                     }
; #pragma unroll
;                     for (int q = 0; q < 4; ++q) {
;                         const u32x2 lo = *(const LAS u32x2*)(CS + l * 256 + (((4 * q + (fq >> 1)) ^ fr) << 4) + (fq & 1) * 8), hi = *(const LAS u32x2*)(CS + l * 256 + (((4 * q + 2 + (fq >> 1)) ^ fr) << 4) + (fq & 1) * 8);
;                         u32x4 c4; c4.x = lo.x; c4.y = lo.y; c4.z = hi.x; c4.w = hi.y; const bf16x8 cfr = __builtin_bit_cast(bf16x8, c4);
;                         acco[0] = __builtin_amdgcn_mfma_f32_16x16x32_bf16(hf[0][q], cfr, acco[0], 0, 0, 0);
;                         acco[1] = __builtin_amdgcn_mfma_f32_16x16x32_bf16(hf[1][q], cfr, acco[1], 0, 0, 0);
;                     }
;                     {
;                         float gg[8]; unpack8(*(const LAS u32x4*)(GS + l * 256 + (((4 * kd + fq) ^ fr) << 4)), gg);
;                         const f32x4 ca = *(const LAS f32x4*)(tab + 32 * kd + 8 * fq), cb = *(const LAS f32x4*)(tab + 32 * kd + 8 * fq + 4);
.LBB0_518:
	v_add3_u32 v141, 0, v141, v195
	v_add_u32_e32 v142, v141, v185
	v_add_u32_e32 v144, v141, v183
	ds_read_b64 v[142:143], v142
	ds_read_b64 v[144:145], v144
	v_add_u32_e32 v146, v141, v187
	ds_read_b64 v[152:153], v146
	ds_read_b32 v162, v214 offset:448
	v_add_u32_e32 v146, v141, v213
	ds_read_b64 v[154:155], v146
	s_waitcnt lgkmcnt(3)
	v_mfma_f32_16x16x32_bf16 v[156:159], v[116:119], v[142:145], 0
	v_add_u32_e32 v146, v141, v212
	v_add_u32_e32 v147, v141, v211
	v_add_u32_e32 v163, v141, v191
	v_mfma_f32_16x16x32_bf16 v[142:145], v[124:127], v[142:145], 0
	ds_read_b64 v[164:165], v146
	ds_read_b64 v[166:167], v147
	ds_read_b64 v[216:217], v163
	v_add_u32_e32 v141, v141, v210
	v_lshlrev_b32_e32 v171, 4, v205
	s_waitcnt lgkmcnt(3)
	v_mfma_f32_16x16x32_bf16 v[156:159], v[112:115], v[152:155], v[156:159]
	ds_read_b64 v[218:219], v141
	v_add_u32_e32 v140, v140, v171
	v_add_u32_e32 v170, 0x61, v180
	v_mfma_f32_16x16x32_bf16 v[142:145], v[120:123], v[152:155], v[142:145]
	v_add_u32_e32 v169, 0x62, v180
	s_mov_b32 s94, s92
	s_waitcnt lgkmcnt(2)
	v_mfma_f32_16x16x32_bf16 v[152:155], v[108:111], v[164:167], v[156:159]
	s_mov_b32 s95, s92
	s_mov_b32 s93, s92
	s_nop 0
	ds_read_b128 v[156:159], v197 offset:384
	v_mfma_f32_16x16x32_bf16 v[142:145], v[128:131], v[164:167], v[142:145]
	ds_read_b128 v[164:167], v140
	s_waitcnt lgkmcnt(1)
	v_sub_f32_e32 v140, v161, v156
	v_mfma_f32_16x16x32_bf16 v[220:223], v[104:107], v[216:219], v[152:155]
	s_waitcnt lgkmcnt(0)
	v_lshlrev_b32_e32 v174, 16, v166
	v_and_b32_e32 v175, 0xffff0000, v166
	v_exp_f32_e32 v166, v140
	v_mfma_f32_16x16x32_bf16 v[216:219], v[132:135], v[216:219], v[142:145]
	ds_read_b128 v[152:155], v197 offset:896
	v_lshlrev_b32_e32 v163, 16, v164
	v_cndmask_b32_e64 v166, 0, v166, s[40:41]
	ds_read_b128 v[144:147], v197 offset:400
	v_mul_f32_e32 v163, v166, v163
	s_waitcnt lgkmcnt(1)
	v_mul_f32_e32 v166, v152, v163
	v_fma_f32 v163, v152, v163, v203
	v_lshlrev_b32_e32 v178, 16, v167
	v_and_b32_e32 v179, 0xffff0000, v167
	ds_read_b128 v[140:143], v197 offset:912
	v_cndmask_b32_e64 v197, v166, v163, s[42:43]
	v_sub_f32_e32 v167, v161, v157
	v_exp_f32_e32 v167, v167
	v_cmp_le_i32_e32 vcc, v170, v160
	v_cmp_eq_u32_e64 s[100:101], v170, v160
	s_xnor_b64 vcc, vcc, s[38:39]
	s_andn2_b64 s[100:101], s[100:101], s[38:39]
	s_or_b64 vcc, vcc, s[100:101]
	v_and_b32_e32 v164, 0xffff0000, v164
	v_sub_f32_e32 v166, v161, v158
	v_cndmask_b32_e32 v163, 0, v167, vcc
	v_mul_f32_e32 v163, v163, v164
	v_cmp_eq_u32_e32 vcc, v170, v160
	v_mul_f32_e32 v164, v153, v163
	v_fma_f32 v163, v153, v163, v203
	s_and_b64 vcc, s[38:39], vcc
	v_cndmask_b32_e32 v200, v164, v163, vcc
	v_exp_f32_e32 v166, v166
	v_lshlrev_b32_e32 v173, 16, v165
	v_add_u32_e32 v167, 0x63, v180
	v_and_b32_e32 v165, 0xffff0000, v165
	v_cmp_le_i32_e32 vcc, v169, v160
	v_cmp_eq_u32_e64 s[100:101], v169, v160
	s_xnor_b64 vcc, vcc, s[38:39]
	s_andn2_b64 s[100:101], s[100:101], s[38:39]
	s_or_b64 vcc, vcc, s[100:101]
	s_waitcnt lgkmcnt(1)
	v_sub_f32_e32 v214, v161, v145
	v_exp_f32_e32 v214, v214
	v_cndmask_b32_e32 v163, 0, v166, vcc
	v_mul_f32_e32 v163, v163, v173
	v_cmp_eq_u32_e32 vcc, v169, v160
	v_mul_f32_e32 v164, v154, v163
	v_fma_f32 v163, v154, v163, v203
	s_and_b64 vcc, s[38:39], vcc
	v_cndmask_b32_e32 v173, v164, v163, vcc
	v_sub_f32_e32 v166, v161, v159
	v_exp_f32_e32 v166, v166
	v_sub_f32_e32 v224, v161, v146
	v_exp_f32_e32 v224, v224
	v_cmp_le_i32_e32 vcc, v167, v160
	v_cmp_eq_u32_e64 s[100:101], v167, v160
	s_xnor_b64 vcc, vcc, s[38:39]
	s_andn2_b64 s[100:101], s[100:101], s[38:39]
	s_or_b64 vcc, vcc, s[100:101]
	v_sub_f32_e32 v225, v161, v147
	v_exp_f32_e32 v225, v225
	v_cndmask_b32_e32 v163, 0, v166, vcc
	v_mul_f32_e32 v163, v163, v165
	v_cmp_eq_u32_e32 vcc, v167, v160
	v_mul_f32_e32 v164, v155, v163
	v_fma_f32 v163, v155, v163, v203
	s_and_b64 vcc, s[38:39], vcc
	v_add_u32_e32 v166, 0x64, v180
	v_cndmask_b32_e32 v201, v164, v163, vcc
	v_sub_f32_e32 v165, v161, v144
	v_exp_f32_e32 v165, v165
	s_nop 1
	v_cmp_le_i32_e32 vcc, v166, v160
	v_cmp_eq_u32_e64 s[100:101], v166, v160
	s_xnor_b64 vcc, vcc, s[38:39]
	s_andn2_b64 s[100:101], s[100:101], s[38:39]
	s_or_b64 vcc, vcc, s[100:101]
	v_cndmask_b32_e32 v163, 0, v165, vcc
	v_mul_f32_e32 v163, v163, v174
	v_cmp_eq_u32_e32 vcc, v166, v160
	s_waitcnt lgkmcnt(0)
; __device__ __forceinline__ unsigned cvt_pk_bf16(float lo, float hi) { const f32x2 v = {lo, hi}; return __builtin_bit_cast(unsigned, __builtin_convertvector(v, bf16x2_t)); }
; __device__ __forceinline__ u32x4 pack8(const float (&f)[8]) { u32x4 w; w.x = cvt_pk_bf16(f[0], f[1]); w.y = cvt_pk_bf16(f[2], f[3]); w.z = cvt_pk_bf16(f[4], f[5]); w.w = cvt_pk_bf16(f[6], f[7]); return w; }
; template <int MODE> __device__ __forceinline__ void ssd_scan_phase(Frame& F, int j, bool ctx_out) {
;     ...
;                         for (int jj = 0; jj < 8; ++jj) { const int s = 32 * kd + 8 * fq + jj; const bool valid = dir == 0 ? (s <= l) : (s >= l);
;                             const float e = valid ? __builtin_amdgcn_exp2f(cl - cs[jj]) : 0.f; m[jj] = gg[jj] * e * ds[jj]; if (dir == 0 && s == l) m[jj] += dsk; }
;                         const bf16x8 mf = __builtin_bit_cast(bf16x8, pack8(m));
;                         accd[0] = __builtin_amdgcn_mfma_f32_16x16x32_bf16(xa, mf, accd[0], 0, 0, 0);
;                         accd[1] = __builtin_amdgcn_mfma_f32_16x16x32_bf16(xb, mf, accd[1], 0, 0, 0);
;                     }
;                     const float el = __builtin_amdgcn_exp2f(cl);
; #pragma unroll
;                     for (int pt = 0; pt < 2; ++pt) { const f32x4 y = accd[pt] + acco[pt] * el; u32x2 o; o.x = cvt_pk_bf16(y[0], y[1]); o.y = cvt_pk_bf16(y[2], y[3]);
;                         *(u32x2*)(yout + (size_t)(row0 + l) * DI + h * 64 + ph * 32 + 16 * pt + 4 * fq) = o; }
;                 }
	v_mul_f32_e32 v164, v140, v163
	v_fma_f32 v163, v140, v163, v203
	s_and_b64 vcc, s[38:39], vcc
	v_add_u32_e32 v165, 0x65, v180
	v_cndmask_b32_e32 v174, v164, v163, vcc
	s_nop 1
	s_nop 1
	v_cmp_le_i32_e32 vcc, v165, v160
	v_cmp_eq_u32_e64 s[100:101], v165, v160
	s_xnor_b64 vcc, vcc, s[38:39]
	s_andn2_b64 s[100:101], s[100:101], s[38:39]
	s_or_b64 vcc, vcc, s[100:101]
	v_cndmask_b32_e32 v163, 0, v214, vcc
	v_mul_f32_e32 v163, v163, v175
	v_cmp_eq_u32_e32 vcc, v165, v160
	v_mul_f32_e32 v164, v141, v163
	v_fma_f32 v163, v141, v163, v203
	s_and_b64 vcc, s[38:39], vcc
	v_cndmask_b32_e32 v175, v164, v163, vcc
	v_add_u32_e32 v164, 0x66, v180
	v_cvt_pk_bf16_f32 v226, v174, v175
	v_exp_f32_e32 v174, v161
	s_nop 1
	v_cmp_le_i32_e32 vcc, v164, v160
	v_cmp_eq_u32_e64 s[100:101], v164, v160
	s_xnor_b64 vcc, vcc, s[38:39]
	s_andn2_b64 s[100:101], s[100:101], s[38:39]
	s_or_b64 vcc, vcc, s[100:101]
	v_cndmask_b32_e32 v163, 0, v224, vcc
	v_mul_f32_e32 v163, v163, v178
	v_cmp_eq_u32_e32 vcc, v164, v160
	v_mul_f32_e32 v178, v142, v163
	v_fma_f32 v163, v142, v163, v203
	s_and_b64 vcc, s[38:39], vcc
	v_cndmask_b32_e32 v178, v178, v163, vcc
	v_add_u32_e32 v163, 0x67, v180
	s_nop 1
	s_nop 1
	v_cmp_le_i32_e32 vcc, v163, v160
	v_cmp_eq_u32_e64 s[100:101], v163, v160
	s_xnor_b64 vcc, vcc, s[38:39]
	s_andn2_b64 s[100:101], s[100:101], s[38:39]
	s_or_b64 vcc, vcc, s[100:101]
	v_cvt_pk_bf16_f32 v224, v197, v200
	s_nop 0
	v_cndmask_b32_e32 v214, 0, v225, vcc
	v_mul_f32_e32 v179, v214, v179
	v_cmp_eq_u32_e32 vcc, v163, v160
	v_mul_f32_e32 v214, v143, v179
	v_fma_f32 v179, v143, v179, v203
	s_and_b64 vcc, s[38:39], vcc
	v_cndmask_b32_e32 v179, v214, v179, vcc
	v_cvt_pk_bf16_f32 v225, v173, v201
	v_cvt_pk_bf16_f32 v227, v178, v179
	v_add_u32_e32 v160, s5, v160
	v_ashrrev_i32_e32 v161, 31, v160
	v_mfma_f32_16x16x32_bf16 v[228:231], v[8:11], v[224:227], v[148:151]
	v_lshlrev_b64 v[160:161], 13, v[160:161]
	v_lshl_add_u64 v[160:161], v[198:199], 0, v[160:161]
	s_and_b64 vcc, exec, s[46:47]
	s_waitcnt vmcnt(7)
	v_mfma_f32_16x16x32_bf16 v[100:103], v[136:139], v[224:227], v[100:103]
	v_mov_b64_e32 v[150:151], s[94:95]
	s_nop 1
	v_pk_fma_f32 v[200:201], v[174:175], v[222:223], v[230:231] op_sel_hi:[0,1,1]
	v_pk_fma_f32 v[220:221], v[174:175], v[220:221], v[228:229] op_sel_hi:[0,1,1]
	v_cvt_pk_bf16_f32 v220, v220, v221
	v_cvt_pk_bf16_f32 v221, v200, v201
	s_nop 0
	v_pk_fma_f32 v[102:103], v[174:175], v[218:219], v[102:103] op_sel_hi:[0,1,1]
	v_pk_fma_f32 v[100:101], v[174:175], v[216:217], v[100:101] op_sel_hi:[0,1,1]
	v_cvt_pk_bf16_f32 v100, v100, v101
	v_cvt_pk_bf16_f32 v101, v102, v103
	global_store_dwordx2 v[160:161], v[220:221], off
	global_store_dwordx2 v[160:161], v[100:101], off offset:32
	v_or_b32_e32 v160, 0x70, v176
	v_lshlrev_b32_e32 v173, 8, v160
	v_mov_b64_e32 v[102:103], s[94:95]
	v_mov_b64_e32 v[148:149], s[92:93]
	v_add_u32_e32 v161, s87, v173
	v_mov_b64_e32 v[100:101], s[92:93]
	s_cbranch_vccz .LBB0_538
	s_and_b64 vcc, exec, s[46:47]
	s_cbranch_vccz .LBB0_539
